# shorten hipcc wave-uniform branch test (sec 7.12): scalar mask inversion via s_not_b64 instead of v_cndmask + v_cmp in the attention tile loop
# speedup vs baseline: 1.0058x; 1.0034x over previous
; #define LAS __attribute__((address_space(3)))
; __device__ __forceinline__ void attn_item(LAS unsigned char* lds, const bf16_t* z, const float* kmean, bf16_t* cat, int b, int h, int j) {
;     ...
;             for (int ks = 0; ks < 4; ++ks) {
;                 const bf16x8 k0 = *(const LAS bf16x8*)(Ks + (ks * 16 + lq) * 72 + quad * 8), k1 = *(const LAS bf16x8*)(Ks + (ks * 16 + lq) * 72 + 32 + quad * 8);
; #pragma unroll
;                 for (int qg = 0; qg < 2; ++qg) { f32x4 a = (f32x4){0.f, 0.f, 0.f, 0.f};
;                     a = __builtin_amdgcn_mfma_f32_16x16x32_bf16(k0, Qf[qg][0], a, 0, 0, 0);
;                     a = __builtin_amdgcn_mfma_f32_16x16x32_bf16(k1, Qf[qg][1], a, 0, 0, 0);
;                     s[ks][qg] = a; } }
;             bf16x8 Pf[2][2];
;             const bool diag = own && (kt * 64 + 63 > wave * 32);
; #pragma unroll
;             for (int qg = 0; qg < 2; ++qg) {
;                 const int qpos = wave * 32 + qg * 16 + lq; const bool selq = own || (((selm[qg] >> blk) & 1) != 0);
;                 if (diag) {
; #pragma unroll
;                     for (int ks = 0; ks < 4; ++ks)
; #pragma unroll
;                         for (int i = 0; i < 4; ++i) { const int kpos = kt * 64 + ks * 16 + quad * 4 + i; s[ks][qg][i] = (kpos <= qpos) ? s[ks][qg][i] : -INFINITY; }
;                 }
.LBB0_1597:
	s_add_i32 s2, s43, 0xffffff80
	s_and_b32 s2, s2, 0x80
	s_mulk_i32 s2, 0x90
	s_add_i32 s2, s2, 0
	v_add3_u32 v131, s2, v124, v122
	v_add3_u32 v130, s2, v125, v122
	v_add3_u32 v129, s2, v123, v122
	v_add_u32_e32 v128, s2, v121
	v_add_u32_e32 v94, v128, v122
	ds_read_b128 v[154:157], v131
	ds_read_b128 v[158:161], v131 offset:64
	ds_read_b128 v[162:165], v130
	ds_read_b128 v[166:169], v130 offset:64
	ds_read_b128 v[170:173], v129
	ds_read_b128 v[174:177], v129 offset:64
	ds_read_b128 v[178:181], v94
	ds_read_b128 v[182:185], v94 offset:64
	s_waitcnt lgkmcnt(7)
	v_mfma_f32_16x16x32_bf16 v[74:77], v[154:157], v[10:13], 0
	s_add_i32 s2, s44, 0xffffff7f
	s_cmp_gt_i32 s2, s81
	v_mfma_f32_16x16x32_bf16 v[58:61], v[154:157], v[18:21], 0
	s_cselect_b64 s[2:3], -1, 0
	s_and_b64 s[2:3], s[36:37], s[2:3]
	v_add_u32_e32 v114, s44, v99
	s_waitcnt lgkmcnt(6)
	v_mfma_f32_16x16x32_bf16 v[82:85], v[158:161], v[14:17], v[74:77]
	v_mfma_f32_16x16x32_bf16 v[78:81], v[158:161], v[22:25], v[58:61]
	s_waitcnt lgkmcnt(5)
	v_mfma_f32_16x16x32_bf16 v[74:77], v[162:165], v[10:13], 0
	s_andn2_b64 vcc, exec, s[2:3]
	v_mfma_f32_16x16x32_bf16 v[58:61], v[162:165], v[18:21], 0
	s_waitcnt lgkmcnt(4)
	v_mfma_f32_16x16x32_bf16 v[86:89], v[166:169], v[14:17], v[74:77]
	v_mfma_f32_16x16x32_bf16 v[62:65], v[166:169], v[22:25], v[58:61]
	s_waitcnt lgkmcnt(3)
	v_mfma_f32_16x16x32_bf16 v[90:93], v[170:173], v[10:13], 0
	v_mfma_f32_16x16x32_bf16 v[58:61], v[170:173], v[18:21], 0
	s_waitcnt lgkmcnt(2)
	v_mfma_f32_16x16x32_bf16 v[90:93], v[174:177], v[14:17], v[90:93]
	v_mfma_f32_16x16x32_bf16 v[58:61], v[174:177], v[22:25], v[58:61]
	s_waitcnt lgkmcnt(1)
	v_mfma_f32_16x16x32_bf16 v[94:97], v[178:181], v[10:13], 0
	v_mfma_f32_16x16x32_bf16 v[74:77], v[178:181], v[18:21], 0
	s_waitcnt lgkmcnt(0)
	v_mfma_f32_16x16x32_bf16 v[94:97], v[182:185], v[14:17], v[94:97]
	v_mfma_f32_16x16x32_bf16 v[74:77], v[182:185], v[22:25], v[74:77]
	v_add_u32_e32 v190, v131, v101
	v_add_u32_e32 v191, v130, v101
	v_add_u32_e32 v200, v129, v101
	v_lshl_add_u32 v201, v99, 1, v128
	v_add_u32_e32 v190, 0x2000, v190
	v_add_u32_e32 v191, 0x2000, v191
	v_add_u32_e32 v200, 0x2000, v200
	v_add_u32_e32 v201, 0x2000, v201
	ds_read2_b64 v[154:157], v190 offset0:128 offset1:132
	ds_read2_b64 v[158:161], v190 offset0:136 offset1:140
	ds_read2_b64 v[162:165], v191 offset0:128 offset1:132
	ds_read2_b64 v[166:169], v191 offset0:136 offset1:140
	ds_read2_b64 v[170:173], v200 offset0:128 offset1:132
	ds_read2_b64 v[174:177], v200 offset0:136 offset1:140
	ds_read2_b64 v[178:181], v201 offset0:128 offset1:132
	ds_read2_b64 v[182:185], v201 offset0:136 offset1:140
	s_not_b64 s[8:9], s[2:3]
	s_cbranch_vccnz .LBB0_1599
	v_add_u32_e32 v115, 0xffffff40, v114
	v_add_u32_e32 v136, 0xffffff43, v114
	v_add_u32_e32 v139, 0xffffff52, v114
	v_add_u32_e32 v137, 0xffffff53, v114
	v_add_u32_e32 v141, 0xffffff61, v114
	v_add_u32_e32 v140, 0xffffff62, v114
	v_add_u32_e32 v138, 0xffffff63, v114
	v_cmp_le_i32_e64 s[10:11], v115, v98
	v_cmp_lt_i32_e64 s[12:13], v115, v98
	v_cmp_le_i32_e64 s[16:17], v136, v98
	v_cmp_le_i32_e64 s[22:23], v139, v98
	v_cmp_le_i32_e64 s[24:25], v137, v98
	v_cmp_le_i32_e64 s[28:29], v141, v98
	v_cmp_le_i32_e64 s[30:31], v140, v98
	v_cmp_le_i32_e64 s[34:35], v138, v98
	v_add_u32_e32 v132, 0xffffff42, v114
	v_add_u32_e32 v134, 0xffffff50, v114
	v_add_u32_e32 v133, 0xffffff51, v114
	v_add_u32_e32 v135, 0xffffff60, v114
	v_cmp_le_i32_e64 s[14:15], v132, v98
	v_cmp_le_i32_e64 s[18:19], v134, v98
	v_cmp_le_i32_e64 s[20:21], v133, v98
	v_cmp_le_i32_e64 s[26:27], v135, v98
	s_nop 1
	v_add_u32_e32 v142, 0xffffff70, v114
	v_cmp_le_i32_e32 vcc, v142, v98
	v_add_u32_e32 v142, 0xffffff71, v114
	v_cndmask_b32_e64 v82, v237, v82, s[10:11]
	v_cndmask_b32_e32 v94, v237, v94, vcc
	v_cmp_le_i32_e32 vcc, v142, v98
	v_add_u32_e32 v142, 0xffffff72, v114
	v_add_u32_e32 v114, 0xffffff73, v114
	v_cndmask_b32_e32 v95, v237, v95, vcc
	v_cmp_le_i32_e32 vcc, v142, v98
	v_cndmask_b32_e64 v83, v237, v83, s[12:13]
	v_cndmask_b32_e64 v84, v237, v84, s[14:15]
	v_cndmask_b32_e32 v96, v237, v96, vcc
	v_cmp_le_i32_e32 vcc, v114, v98
	v_cndmask_b32_e64 v85, v237, v85, s[16:17]
	v_cndmask_b32_e64 v86, v237, v86, s[18:19]
	v_cndmask_b32_e64 v87, v237, v87, s[20:21]
	v_cndmask_b32_e64 v88, v237, v88, s[22:23]
	v_cndmask_b32_e64 v89, v237, v89, s[24:25]
	v_cndmask_b32_e64 v90, v237, v90, s[26:27]
	v_cndmask_b32_e64 v91, v237, v91, s[28:29]
	v_cndmask_b32_e64 v92, v237, v92, s[30:31]
	v_cndmask_b32_e64 v93, v237, v93, s[34:35]
	v_cndmask_b32_e32 v97, v237, v97, vcc
